# norm phases: per-lane gamma/scale/shift vectors loaded once before the row loop instead of 8 serialized load+wait groups per row pair
# speedup vs baseline: 1.0055x; 1.0055x over previous
.LBB0_908:
	s_or_b64 exec, exec, s[6:7]
	v_readlane_b32 s0, v255, 10
	v_readlane_b32 s1, v255, 11
	s_waitcnt lgkmcnt(0)
	v_mov_b32_e32 v0, v254
	v_mov_b64_e32 v[2:3], s[0:1]
	s_barrier
	flat_load_dwordx2 v[2:3], v[2:3] offset:56 sc0 sc1
	s_waitcnt vmcnt(0)
	v_readfirstlane_b32 s0, v0
	s_ashr_i32 s6, s0, 6
	v_readlane_b32 s0, v255, 6
	s_lshl_b32 s52, s30, 4
	s_add_i32 s20, s6, s0
	s_cmpk_lt_i32 s20, 0x2000
	s_waitcnt lgkmcnt(0)
	v_readfirstlane_b32 s5, v3
	v_readfirstlane_b32 s4, v2
	s_cbranch_scc0 .LBB0_927
	v_lshlrev_b32_e32 v1, 4, v0
	v_and_b32_e32 v64, 0x3f0, v1
	v_mbcnt_lo_u32_b32 v1, -1, 0
	v_mbcnt_hi_u32_b32 v1, -1, v1
	v_and_b32_e32 v2, 64, v1
	v_add_u32_e32 v2, 64, v2
	v_xor_b32_e32 v3, 1, v1
	v_cmp_lt_i32_e32 vcc, v3, v2
	s_add_u32 s8, s26, 0x6000
	s_addc_u32 s9, s27, 0
	v_cndmask_b32_e32 v3, v1, v3, vcc
	v_lshlrev_b32_e32 v116, 2, v3
	v_xor_b32_e32 v3, 2, v1
	v_cmp_lt_i32_e32 vcc, v3, v2
	s_add_u32 s10, s26, 0x8000
	v_mov_b32_e32 v65, 0
	v_cndmask_b32_e32 v3, v1, v3, vcc
	v_lshlrev_b32_e32 v117, 2, v3
	v_xor_b32_e32 v3, 4, v1
	v_cmp_lt_i32_e32 vcc, v3, v2
	s_load_dwordx2 s[0:1], s[88:89], 0x168
	s_addc_u32 s11, s27, 0
	v_cndmask_b32_e32 v3, v1, v3, vcc
	v_lshlrev_b32_e32 v118, 2, v3
	v_xor_b32_e32 v3, 8, v1
	v_cmp_lt_i32_e32 vcc, v3, v2
	s_waitcnt lgkmcnt(0)
	v_lshl_add_u64 v[66:67], s[0:1], 0, v[64:65]
	v_lshl_add_u64 v[68:69], s[4:5], 0, v[64:65]
	v_cndmask_b32_e32 v3, v1, v3, vcc
	v_lshlrev_b32_e32 v119, 2, v3
	v_xor_b32_e32 v3, 16, v1
	v_cmp_lt_i32_e32 vcc, v3, v2
	v_lshl_add_u64 v[70:71], s[10:11], 0, v[64:65]
	v_lshl_add_u64 v[72:73], s[8:9], 0, v[64:65]
	v_cndmask_b32_e32 v3, v1, v3, vcc
	v_lshlrev_b32_e32 v120, 2, v3
	v_xor_b32_e32 v3, 32, v1
	v_cmp_lt_i32_e32 vcc, v3, v2
	v_or_b32_e32 v2, 0x400, v64
	v_and_b32_e32 v0, 63, v0
	v_cndmask_b32_e32 v1, v1, v3, vcc
	v_mov_b32_e32 v3, v65
	v_lshl_add_u64 v[74:75], s[10:11], 0, v[2:3]
	v_lshl_add_u64 v[76:77], s[8:9], 0, v[2:3]
	v_or_b32_e32 v2, 0x800, v64
	v_lshl_add_u64 v[78:79], s[10:11], 0, v[2:3]
	v_lshl_add_u64 v[80:81], s[8:9], 0, v[2:3]
	v_or_b32_e32 v2, 0xc00, v64
	v_lshl_add_u64 v[82:83], s[10:11], 0, v[2:3]
	v_lshl_add_u64 v[84:85], s[8:9], 0, v[2:3]
	v_or_b32_e32 v2, 0x1000, v64
	v_lshl_add_u64 v[86:87], s[4:5], 0, v[2:3]
	v_lshl_add_u64 v[88:89], s[10:11], 0, v[2:3]
	v_lshl_add_u64 v[90:91], s[8:9], 0, v[2:3]
	v_or_b32_e32 v2, 0x1400, v64
	v_lshl_add_u64 v[92:93], s[4:5], 0, v[2:3]
	v_lshl_add_u64 v[94:95], s[10:11], 0, v[2:3]
	v_lshl_add_u64 v[96:97], s[8:9], 0, v[2:3]
	v_or_b32_e32 v2, 0x1800, v64
	v_or_b32_e32 v64, 0x1c00, v64
	v_lshl_add_u64 v[98:99], s[4:5], 0, v[2:3]
	v_lshl_add_u64 v[104:105], s[4:5], 0, v[64:65]
	s_add_i32 s4, s20, s22
	s_ashr_i32 s5, s4, 31
	s_lshl_b64 s[4:5], s[4:5], 12
	v_lshl_add_u64 v[100:101], s[10:11], 0, v[2:3]
	v_lshl_add_u64 v[106:107], s[10:11], 0, v[64:65]
	s_add_u32 s10, s26, s4
	s_addc_u32 s11, s27, s5
	s_ashr_i32 s53, s52, 31
	v_readlane_b32 s4, v255, 6
	s_lshl_b64 s[12:13], s[52:53], 12
	s_ashr_i32 s5, s6, 31
	s_ashr_i32 s7, s4, 31
	s_add_u32 s4, s6, s4
	s_addc_u32 s5, s5, s7
	s_lshl_b64 s[6:7], s[4:5], 12
	s_add_u32 s6, s26, s6
	s_addc_u32 s7, s27, s7
	s_add_u32 s14, s6, 0x7200800
	s_addc_u32 s15, s7, 0
	s_lshl_b64 s[4:5], s[4:5], 13
	s_add_u32 s0, s0, s4
	v_lshlrev_b32_e32 v121, 2, v1
	v_lshl_add_u64 v[108:109], s[8:9], 0, v[64:65]
	v_lshlrev_b32_e32 v64, 3, v0
	v_lshlrev_b32_e32 v0, 4, v0
	v_mov_b32_e32 v1, v65
	s_addc_u32 s1, s1, s5
	v_lshl_add_u64 v[0:1], s[0:1], 0, v[0:1]
	s_mov_b64 s[0:1], 0x1c00
	s_movk_i32 s21, 0x1000
	v_lshl_add_u64 v[102:103], s[8:9], 0, v[2:3]
	v_lshl_add_u64 v[110:111], v[0:1], 0, s[0:1]
	s_lshl_b64 s[16:17], s[52:53], 13
	v_mov_b32_e32 v122, 0x358637bd
	s_mov_b32 s0, 0xf800000
	v_mov_b32_e32 v123, 0x260
	flat_load_dwordx4 v[150:153], v[68:69]
	global_load_dwordx4 v[154:157], v[70:71], off
	global_load_dwordx4 v[158:161], v[72:73], off
	global_load_dwordx4 v[162:165], v[74:75], off
	flat_load_dwordx4 v[166:169], v[68:69] offset:1024
	global_load_dwordx4 v[170:173], v[76:77], off
	global_load_dwordx4 v[174:177], v[78:79], off
	flat_load_dwordx4 v[178:181], v[68:69] offset:2048
	global_load_dwordx4 v[182:185], v[80:81], off
	global_load_dwordx4 v[186:189], v[82:83], off
	flat_load_dwordx4 v[190:193], v[68:69] offset:3072
	global_load_dwordx4 v[194:197], v[84:85], off
	global_load_dwordx4 v[198:201], v[88:89], off
	flat_load_dwordx4 v[202:205], v[86:87]
	global_load_dwordx4 v[206:209], v[90:91], off
	global_load_dwordx4 v[210:213], v[94:95], off
	flat_load_dwordx4 v[214:217], v[92:93]
	global_load_dwordx4 v[218:221], v[96:97], off
	global_load_dwordx4 v[222:225], v[100:101], off
	flat_load_dwordx4 v[226:229], v[98:99]
	global_load_dwordx4 v[230:233], v[102:103], off
	global_load_dwordx4 v[234:237], v[106:107], off
	flat_load_dwordx4 v[238:241], v[104:105]
	global_load_dwordx4 v[242:245], v[108:109], off
	s_waitcnt vmcnt(0) lgkmcnt(0)
	s_branch .LBB0_911

.LBB0_911:
	v_add_co_u32_e32 v4, vcc, 0xfffff000, v110
	s_add_i32 s1, s22, s20
	s_nop 0
	v_addc_co_u32_e32 v5, vcc, -1, v111, vcc
	s_cmpk_lt_i32 s1, 0x2000
	global_load_dwordx4 v[32:35], v[110:111], off offset:-4096
	global_load_dwordx4 v[24:27], v[110:111], off offset:-3072
	global_load_dwordx4 v[16:19], v[110:111], off offset:-2048
	global_load_dwordx4 v[8:11], v[110:111], off offset:-1024
	global_load_dwordx4 v[0:3], v[110:111], off
	global_load_dwordx4 v[56:59], v[4:5], off offset:-3072
	global_load_dwordx4 v[48:51], v[4:5], off offset:-2048
	global_load_dwordx4 v[40:43], v[4:5], off offset:-1024
	s_cselect_b64 s[18:19], -1, 0
	s_and_b64 s[4:5], s[18:19], exec
	s_cselect_b32 s4, s1, s20
	s_ashr_i32 s5, s4, 31
	s_lshl_b64 s[4:5], s[4:5], 13
	v_lshl_add_u64 v[4:5], v[66:67], 0, s[4:5]
	global_load_dwordx4 v[60:63], v[4:5], off
	global_load_dwordx4 v[52:55], v[4:5], off offset:1024
	global_load_dwordx4 v[44:47], v[4:5], off offset:2048
	global_load_dwordx4 v[36:39], v[4:5], off offset:3072
	v_add_co_u32_e32 v4, vcc, s21, v4
	s_cmpk_gt_i32 s1, 0x1fff
	s_nop 0
	v_addc_co_u32_e32 v5, vcc, 0, v5, vcc
	global_load_dwordx4 v[28:31], v[4:5], off
	global_load_dwordx4 v[20:23], v[4:5], off offset:1024
	global_load_dwordx4 v[12:15], v[4:5], off offset:2048
	s_nop 0
	global_load_dwordx4 v[4:7], v[4:5], off offset:3072
	s_waitcnt vmcnt(15)
	v_mul_f32_e32 v124, v33, v33
	s_waitcnt vmcnt(14)
	v_mul_f32_e32 v125, v25, v25
	v_fmac_f32_e32 v124, v32, v32
	s_waitcnt vmcnt(10)
	v_mul_f32_e32 v127, v57, v57
	s_waitcnt vmcnt(9)
	v_mul_f32_e32 v128, v49, v49
	s_waitcnt vmcnt(8)
	v_mul_f32_e32 v129, v41, v41
	v_fmac_f32_e32 v127, v56, v56
	v_fmac_f32_e32 v128, v48, v48
	v_fmac_f32_e32 v129, v40, v40
	v_fmac_f32_e32 v127, v58, v58
	v_fmac_f32_e32 v128, v50, v50
	v_fmac_f32_e32 v129, v42, v42
	v_fmac_f32_e32 v127, v59, v59
	v_fmac_f32_e32 v128, v51, v51
	v_fmac_f32_e32 v129, v43, v43
	v_add_f32_e32 v127, v127, v128
	v_mul_f32_e32 v126, v17, v17
	v_fmac_f32_e32 v125, v24, v24
	v_fmac_f32_e32 v124, v34, v34
	v_add_f32_e32 v127, v127, v129
	s_waitcnt vmcnt(7)
	v_mul_f32_e32 v128, v61, v61
	s_waitcnt vmcnt(6)
	v_mul_f32_e32 v129, v53, v53
	v_mov_b32_e32 v114, v9
	v_mov_b32_e32 v115, v1
	v_fmac_f32_e32 v126, v16, v16
	v_fmac_f32_e32 v125, v26, v26
	v_fmac_f32_e32 v124, v35, v35
	s_waitcnt vmcnt(5)
	v_mul_f32_e32 v130, v45, v45
	v_fmac_f32_e32 v128, v60, v60
	v_fmac_f32_e32 v129, v52, v52
	v_mov_b32_e32 v112, v8
	v_mov_b32_e32 v113, v0
	v_pk_mul_f32 v[114:115], v[114:115], v[114:115]
	v_fmac_f32_e32 v126, v18, v18
	v_fmac_f32_e32 v125, v27, v27
	v_add_f32_e32 v124, v127, v124
	s_waitcnt vmcnt(4)
	v_mul_f32_e32 v127, v37, v37
	v_fmac_f32_e32 v130, v44, v44
	v_fmac_f32_e32 v128, v62, v62
	v_fmac_f32_e32 v129, v54, v54
	v_fmac_f32_e32 v126, v19, v19
	v_fmac_f32_e32 v127, v36, v36
	v_add_f32_e32 v124, v124, v125
	v_fmac_f32_e32 v130, v46, v46
	s_waitcnt vmcnt(3)
	v_mul_f32_e32 v125, v29, v29
	v_fmac_f32_e32 v128, v63, v63
	v_fmac_f32_e32 v129, v55, v55
	v_pk_fma_f32 v[112:113], v[112:113], v[112:113], v[114:115]
	v_mov_b32_e32 v114, v10
	v_mov_b32_e32 v115, v2
	v_fmac_f32_e32 v127, v38, v38
	v_add_f32_e32 v124, v124, v126
	s_waitcnt vmcnt(2)
	v_mul_f32_e32 v126, v21, v21
	v_fmac_f32_e32 v130, v47, v47
	v_fmac_f32_e32 v125, v28, v28
	v_add_f32_e32 v128, v128, v129
	v_pk_fma_f32 v[112:113], v[114:115], v[114:115], v[112:113]
	v_mov_b32_e32 v114, v11
	v_mov_b32_e32 v115, v3
	v_fmac_f32_e32 v127, v39, v39
	v_fmac_f32_e32 v126, v20, v20
	v_fmac_f32_e32 v125, v30, v30
	v_add_f32_e32 v128, v128, v130
	v_pk_fma_f32 v[112:113], v[114:115], v[114:115], v[112:113]
	v_fmac_f32_e32 v126, v22, v22
	v_fmac_f32_e32 v125, v31, v31
	v_add_f32_e32 v127, v128, v127
	v_add_f32_e32 v112, v124, v112
	v_fmac_f32_e32 v126, v23, v23
	v_add_f32_e32 v125, v127, v125
	v_add_f32_e32 v124, v112, v113
	v_add_f32_e32 v125, v125, v126
	ds_bpermute_b32 v126, v116, v124
	s_waitcnt vmcnt(1)
	v_mov_b32_e32 v114, v13
	s_waitcnt vmcnt(0)
	v_mov_b32_e32 v115, v5
	v_mov_b32_e32 v112, v12
	v_mov_b32_e32 v113, v4
	s_waitcnt lgkmcnt(0)
	v_add_f32_e32 v124, v124, v126
	ds_bpermute_b32 v126, v117, v124
	v_pk_mul_f32 v[114:115], v[114:115], v[114:115]
	v_mov_b64_e32 v[128:129], v[150:151]
	v_mov_b64_e32 v[130:131], v[152:153]
	v_pk_fma_f32 v[112:113], v[112:113], v[112:113], v[114:115]
	v_mov_b32_e32 v114, v14
	v_mov_b32_e32 v115, v6
	v_pk_fma_f32 v[112:113], v[114:115], v[114:115], v[112:113]
	v_mov_b32_e32 v114, v15
	v_mov_b32_e32 v115, v7
	v_pk_fma_f32 v[112:113], v[114:115], v[114:115], v[112:113]
	s_waitcnt lgkmcnt(0)
	v_add_f32_e32 v114, v124, v126
	v_add_f32_e32 v112, v125, v112
	v_mov_b64_e32 v[124:125], v[154:155]
	v_mov_b64_e32 v[126:127], v[156:157]
	v_mov_b64_e32 v[132:133], v[158:159]
	v_mov_b64_e32 v[134:135], v[160:161]
	ds_bpermute_b32 v115, v118, v114
	v_add_f32_e32 v112, v112, v113
	ds_bpermute_b32 v113, v116, v112
	s_waitcnt lgkmcnt(0)
	v_add_f32_e32 v114, v114, v115
	ds_bpermute_b32 v115, v119, v114
	v_add_f32_e32 v112, v112, v113
	ds_bpermute_b32 v113, v117, v112
	s_waitcnt lgkmcnt(0)
	v_add_f32_e32 v114, v114, v115
	ds_bpermute_b32 v115, v120, v114
	v_add_f32_e32 v112, v112, v113
	ds_bpermute_b32 v113, v118, v112
	s_waitcnt lgkmcnt(0)
	v_add_f32_e32 v114, v114, v115
	ds_bpermute_b32 v115, v121, v114
	v_add_f32_e32 v112, v112, v113
	ds_bpermute_b32 v113, v119, v112
	s_waitcnt lgkmcnt(0)
	v_add_f32_e32 v114, v114, v115
	v_fmamk_f32 v114, v114, 0x3a000000, v122
	v_mul_f32_e32 v115, 0x4f800000, v114
	v_cmp_gt_f32_e32 vcc, s0, v114
	v_add_f32_e32 v112, v112, v113
	ds_bpermute_b32 v113, v120, v112
	v_cndmask_b32_e32 v114, v114, v115, vcc
	v_sqrt_f32_e32 v115, v114
	s_waitcnt lgkmcnt(0)
	v_add_f32_e32 v112, v112, v113
	v_add_u32_e32 v136, -1, v115
	v_fma_f32 v137, -v136, v115, v114
	v_cmp_ge_f32_e64 s[6:7], 0, v137
	v_add_u32_e32 v137, 1, v115
	ds_bpermute_b32 v113, v121, v112
	v_cndmask_b32_e64 v136, v115, v136, s[6:7]
	v_fma_f32 v115, -v137, v115, v114
	v_cmp_lt_f32_e64 s[6:7], 0, v115
	s_waitcnt lgkmcnt(0)
	v_add_f32_e32 v112, v112, v113
	v_cndmask_b32_e64 v115, v136, v137, s[6:7]
	v_mul_f32_e32 v136, 0x37800000, v115
	v_cndmask_b32_e32 v115, v115, v136, vcc
	v_cmp_class_f32_e32 vcc, v114, v123
	v_fmamk_f32 v112, v112, 0x3a000000, v122
	v_mul_f32_e32 v138, 0x4f800000, v112
	v_cndmask_b32_e32 v114, v115, v114, vcc
	v_div_scale_f32 v115, s[4:5], v114, v114, 1.0
	v_rcp_f32_e32 v136, v115
	v_cmp_gt_f32_e64 s[6:7], s0, v112
	v_fma_f32 v113, -v115, v136, 1.0
	s_nop 0
	v_cndmask_b32_e64 v112, v112, v138, s[6:7]
	v_fmac_f32_e32 v136, v113, v136
	v_div_scale_f32 v113, vcc, 1.0, v114, 1.0
	v_sqrt_f32_e32 v138, v112
	v_mul_f32_e32 v137, v113, v136
	v_fma_f32 v139, -v115, v137, v113
	v_fmac_f32_e32 v137, v139, v136
	v_fma_f32 v113, -v115, v137, v113
	v_add_u32_e32 v115, -1, v138
	v_fma_f32 v139, -v115, v138, v112
	v_cmp_ge_f32_e64 s[8:9], 0, v139
	v_add_u32_e32 v139, 1, v138
	v_div_fmas_f32 v113, v113, v136, v137
	v_cndmask_b32_e64 v115, v138, v115, s[8:9]
	v_fma_f32 v138, -v139, v138, v112
	v_cmp_lt_f32_e64 s[8:9], 0, v138
	v_div_fixup_f32 v114, v113, v114, 1.0
	v_pk_add_f32 v[126:127], v[126:127], 1.0 op_sel_hi:[1,0]
	v_cndmask_b32_e64 v115, v115, v139, s[8:9]
	v_mul_f32_e32 v138, 0x37800000, v115
	v_cndmask_b32_e64 v115, v115, v138, s[6:7]
	v_cmp_class_f32_e64 s[6:7], v112, v123
	v_pk_add_f32 v[124:125], v[124:125], 1.0 op_sel_hi:[1,0]
	v_pk_mul_f32 v[126:127], v[130:131], v[126:127]
	v_cndmask_b32_e64 v112, v115, v112, s[6:7]
	v_div_scale_f32 v115, s[4:5], v112, v112, 1.0
	v_rcp_f32_e32 v138, v115
	v_pk_mul_f32 v[124:125], v[128:129], v[124:125]
	v_pk_mul_f32 v[56:57], v[114:115], v[56:57] op_sel_hi:[0,1]
	v_pk_mul_f32 v[58:59], v[114:115], v[58:59] op_sel_hi:[0,1]
	v_fma_f32 v113, -v115, v138, 1.0
	v_fmac_f32_e32 v138, v113, v138
	v_div_scale_f32 v113, vcc, 1.0, v112, 1.0
	v_mul_f32_e32 v136, v113, v138
	v_fma_f32 v137, -v115, v136, v113
	v_fmac_f32_e32 v136, v137, v138
	v_fma_f32 v113, -v115, v136, v113
	v_div_fmas_f32 v113, v113, v138, v136
	v_div_fixup_f32 v112, v113, v112, 1.0
	v_pk_fma_f32 v[58:59], v[126:127], v[58:59], v[134:135]
	v_pk_fma_f32 v[56:57], v[124:125], v[56:57], v[132:133]
	v_pk_mul_f32 v[60:61], v[112:113], v[60:61] op_sel_hi:[0,1]
	v_pk_mul_f32 v[62:63], v[112:113], v[62:63] op_sel_hi:[0,1]
	v_pk_fma_f32 v[60:61], v[124:125], v[60:61], v[132:133]
	s_nop 1
	v_cvt_pk_bf16_f32 v56, v56, v57
	s_nop 1
	v_cvt_pk_bf16_f32 v57, v58, v59
	v_lshl_add_u64 v[58:59], s[14:15], 0, v[64:65]
	v_pk_fma_f32 v[62:63], v[126:127], v[62:63], v[134:135]
	s_nop 1
	v_cvt_pk_bf16_f32 v60, v60, v61
	s_nop 0
	s_nop 1
	v_cvt_pk_bf16_f32 v61, v62, v63
	global_store_dwordx2 v[58:59], v[56:57], off offset:-2048
	v_lshl_add_u64 v[56:57], s[10:11], 0, v[64:65]
	s_cbranch_scc1 .LBB0_913
	v_add_co_u32_e32 v62, vcc, 0x7200000, v56
	s_nop 1
	v_addc_co_u32_e32 v63, vcc, 0, v57, vcc
	global_store_dwordx2 v[62:63], v[60:61], off
.LBB0_913:
	v_mov_b64_e32 v[124:125], v[162:163]
	v_mov_b64_e32 v[126:127], v[164:165]
	v_mov_b64_e32 v[128:129], v[166:167]
	v_mov_b64_e32 v[130:131], v[168:169]
	v_mov_b64_e32 v[132:133], v[170:171]
	v_mov_b64_e32 v[134:135], v[172:173]
	v_mov_b32_e32 v115, v114
	v_mov_b32_e32 v113, v112
	v_mov_b32_e32 v60, v114
	v_mov_b32_e32 v61, v114
	v_mov_b32_e32 v62, v112
	v_mov_b32_e32 v63, v112
	v_cndmask_b32_e64 v136, 0, 1, s[18:19]
	v_pk_mul_f32 v[48:49], v[114:115], v[48:49]
	v_pk_mul_f32 v[50:51], v[60:61], v[50:51]
	v_pk_mul_f32 v[54:55], v[62:63], v[54:55]
	v_pk_mul_f32 v[52:53], v[112:113], v[52:53]
	v_cmp_ne_u32_e64 s[6:7], 1, v136
	s_andn2_b64 vcc, exec, s[18:19]
	v_pk_add_f32 v[124:125], v[124:125], 1.0 op_sel_hi:[1,0]
	v_pk_add_f32 v[126:127], v[126:127], 1.0 op_sel_hi:[1,0]
	s_waitcnt lgkmcnt(0)
	v_pk_mul_f32 v[124:125], v[128:129], v[124:125]
	v_pk_mul_f32 v[126:127], v[130:131], v[126:127]
	v_pk_fma_f32 v[48:49], v[124:125], v[48:49], v[132:133]
	v_pk_fma_f32 v[50:51], v[126:127], v[50:51], v[134:135]
	v_pk_fma_f32 v[54:55], v[126:127], v[54:55], v[134:135]
	v_pk_fma_f32 v[52:53], v[124:125], v[52:53], v[132:133]
	s_nop 1
	v_cvt_pk_bf16_f32 v124, v48, v49
	s_nop 1
	v_cvt_pk_bf16_f32 v125, v50, v51
	s_nop 0
	s_nop 1
	v_cvt_pk_bf16_f32 v48, v52, v53
	s_nop 1
	v_cvt_pk_bf16_f32 v49, v54, v55
	global_store_dwordx2 v[58:59], v[124:125], off offset:-1536
	s_cbranch_vccnz .LBB0_915
	v_add_co_u32_e32 v50, vcc, 0x7200000, v56
	s_nop 1
	v_addc_co_u32_e32 v51, vcc, 0, v57, vcc
	global_store_dwordx2 v[50:51], v[48:49], off offset:512
.LBB0_915:
	v_mov_b64_e32 v[48:49], v[174:175]
	v_mov_b64_e32 v[50:51], v[176:177]
	s_nop 0
	v_mov_b64_e32 v[52:53], v[178:179]
	v_mov_b64_e32 v[54:55], v[180:181]
	v_mov_b64_e32 v[124:125], v[182:183]
	v_mov_b64_e32 v[126:127], v[184:185]
	v_pk_mul_f32 v[40:41], v[114:115], v[40:41]
	v_pk_mul_f32 v[42:43], v[60:61], v[42:43]
	v_pk_mul_f32 v[46:47], v[62:63], v[46:47]
	v_pk_mul_f32 v[44:45], v[112:113], v[44:45]
	s_and_b64 vcc, exec, s[6:7]
	v_pk_add_f32 v[48:49], v[48:49], 1.0 op_sel_hi:[1,0]
	v_pk_add_f32 v[50:51], v[50:51], 1.0 op_sel_hi:[1,0]
	s_waitcnt lgkmcnt(0)
	v_pk_mul_f32 v[48:49], v[52:53], v[48:49]
	v_pk_mul_f32 v[50:51], v[54:55], v[50:51]
	v_pk_fma_f32 v[40:41], v[48:49], v[40:41], v[124:125]
	v_pk_fma_f32 v[42:43], v[50:51], v[42:43], v[126:127]
	v_pk_fma_f32 v[46:47], v[50:51], v[46:47], v[126:127]
	v_pk_fma_f32 v[44:45], v[48:49], v[44:45], v[124:125]
	s_nop 1
	v_cvt_pk_bf16_f32 v48, v40, v41
	s_nop 1
	v_cvt_pk_bf16_f32 v49, v42, v43
	s_nop 0
	s_nop 1
	v_cvt_pk_bf16_f32 v40, v44, v45
	s_nop 1
	v_cvt_pk_bf16_f32 v41, v46, v47
	global_store_dwordx2 v[58:59], v[48:49], off offset:-1024
	s_cbranch_vccnz .LBB0_917
	v_add_co_u32_e32 v42, vcc, 0x7200000, v56
	s_nop 1
	v_addc_co_u32_e32 v43, vcc, 0, v57, vcc
	global_store_dwordx2 v[42:43], v[40:41], off offset:1024
.LBB0_917:
	v_mov_b64_e32 v[42:43], v[186:187]
	v_mov_b64_e32 v[44:45], v[188:189]
	s_nop 0
	v_mov_b64_e32 v[46:47], v[190:191]
	v_mov_b64_e32 v[48:49], v[192:193]
	v_mov_b64_e32 v[50:51], v[194:195]
	v_mov_b64_e32 v[52:53], v[196:197]
	v_mov_b32_e32 v40, v114
	v_mov_b32_e32 v41, v114
	v_pk_mul_f32 v[54:55], v[114:115], v[32:33]
	v_mov_b32_e32 v32, v112
	v_mov_b32_e32 v33, v112
	v_pk_mul_f32 v[34:35], v[40:41], v[34:35]
	v_pk_mul_f32 v[36:37], v[112:113], v[36:37]
	v_pk_mul_f32 v[38:39], v[32:33], v[38:39]
	s_and_b64 vcc, exec, s[6:7]
	v_pk_add_f32 v[44:45], v[44:45], 1.0 op_sel_hi:[1,0]
	v_pk_add_f32 v[42:43], v[42:43], 1.0 op_sel_hi:[1,0]
	s_waitcnt lgkmcnt(0)
	v_pk_mul_f32 v[44:45], v[48:49], v[44:45]
	v_pk_mul_f32 v[42:43], v[46:47], v[42:43]
	v_pk_fma_f32 v[34:35], v[44:45], v[34:35], v[52:53]
	v_pk_fma_f32 v[46:47], v[42:43], v[54:55], v[50:51]
	v_pk_fma_f32 v[38:39], v[44:45], v[38:39], v[52:53]
	v_pk_fma_f32 v[36:37], v[42:43], v[36:37], v[50:51]
	s_nop 1
	v_cvt_pk_bf16_f32 v42, v46, v47
	s_nop 1
	v_cvt_pk_bf16_f32 v43, v34, v35
	s_nop 0
	s_nop 1
	v_cvt_pk_bf16_f32 v34, v36, v37
	s_nop 1
	v_cvt_pk_bf16_f32 v35, v38, v39
	global_store_dwordx2 v[58:59], v[42:43], off offset:-512
	s_cbranch_vccnz .LBB0_919
	v_add_co_u32_e32 v36, vcc, 0x7200000, v56
	s_nop 1
	v_addc_co_u32_e32 v37, vcc, 0, v57, vcc
	global_store_dwordx2 v[36:37], v[34:35], off offset:1536
.LBB0_919:
	v_mov_b64_e32 v[34:35], v[198:199]
	v_mov_b64_e32 v[36:37], v[200:201]
	s_nop 0
	v_mov_b64_e32 v[42:43], v[202:203]
	v_mov_b64_e32 v[44:45], v[204:205]
	v_mov_b64_e32 v[46:47], v[206:207]
	v_mov_b64_e32 v[48:49], v[208:209]
	v_pk_mul_f32 v[24:25], v[114:115], v[24:25]
	v_pk_mul_f32 v[30:31], v[32:33], v[30:31]
	v_pk_mul_f32 v[26:27], v[40:41], v[26:27]
	v_pk_mul_f32 v[28:29], v[112:113], v[28:29]
	s_and_b64 vcc, exec, s[6:7]
	v_pk_add_f32 v[34:35], v[34:35], 1.0 op_sel_hi:[1,0]
	v_pk_add_f32 v[32:33], v[36:37], 1.0 op_sel_hi:[1,0]
	s_waitcnt lgkmcnt(0)
	v_pk_mul_f32 v[34:35], v[42:43], v[34:35]
	v_pk_mul_f32 v[32:33], v[44:45], v[32:33]
	v_pk_fma_f32 v[24:25], v[34:35], v[24:25], v[46:47]
	v_pk_fma_f32 v[26:27], v[32:33], v[26:27], v[48:49]
	v_pk_fma_f32 v[30:31], v[32:33], v[30:31], v[48:49]
	v_pk_fma_f32 v[28:29], v[34:35], v[28:29], v[46:47]
	s_nop 1
	v_cvt_pk_bf16_f32 v32, v24, v25
	s_nop 1
	v_cvt_pk_bf16_f32 v33, v26, v27
	s_nop 0
	s_nop 1
	v_cvt_pk_bf16_f32 v24, v28, v29
	s_nop 1
	v_cvt_pk_bf16_f32 v25, v30, v31
	global_store_dwordx2 v[58:59], v[32:33], off
	s_cbranch_vccnz .LBB0_921
	v_add_co_u32_e32 v26, vcc, 0x7200000, v56
	s_nop 1
	v_addc_co_u32_e32 v27, vcc, 0, v57, vcc
	global_store_dwordx2 v[26:27], v[24:25], off offset:2048
.LBB0_921:
	v_mov_b64_e32 v[26:27], v[210:211]
	v_mov_b64_e32 v[28:29], v[212:213]
	s_nop 0
	v_mov_b64_e32 v[30:31], v[214:215]
	v_mov_b64_e32 v[32:33], v[216:217]
	v_mov_b64_e32 v[34:35], v[218:219]
	v_mov_b64_e32 v[36:37], v[220:221]
	v_mov_b32_e32 v24, v114
	v_mov_b32_e32 v25, v114
	v_pk_mul_f32 v[38:39], v[114:115], v[16:17]
	v_mov_b32_e32 v16, v112
	v_mov_b32_e32 v17, v112
	v_pk_mul_f32 v[18:19], v[24:25], v[18:19]
	v_pk_mul_f32 v[20:21], v[112:113], v[20:21]
	v_pk_mul_f32 v[22:23], v[16:17], v[22:23]
	s_and_b64 vcc, exec, s[6:7]
	v_pk_add_f32 v[28:29], v[28:29], 1.0 op_sel_hi:[1,0]
	v_pk_add_f32 v[26:27], v[26:27], 1.0 op_sel_hi:[1,0]
	s_waitcnt lgkmcnt(0)
	v_pk_mul_f32 v[28:29], v[32:33], v[28:29]
	v_pk_mul_f32 v[26:27], v[30:31], v[26:27]
	v_pk_fma_f32 v[18:19], v[28:29], v[18:19], v[36:37]
	v_pk_fma_f32 v[30:31], v[26:27], v[38:39], v[34:35]
	v_pk_fma_f32 v[22:23], v[28:29], v[22:23], v[36:37]
	v_pk_fma_f32 v[20:21], v[26:27], v[20:21], v[34:35]
	s_nop 1
	v_cvt_pk_bf16_f32 v26, v30, v31
	s_nop 1
	v_cvt_pk_bf16_f32 v27, v18, v19
	s_nop 0
	s_nop 1
	v_cvt_pk_bf16_f32 v18, v20, v21
	s_nop 1
	v_cvt_pk_bf16_f32 v19, v22, v23
	global_store_dwordx2 v[58:59], v[26:27], off offset:512
	s_cbranch_vccnz .LBB0_923
	v_add_co_u32_e32 v20, vcc, 0x7200000, v56
	s_nop 1
	v_addc_co_u32_e32 v21, vcc, 0, v57, vcc
	global_store_dwordx2 v[20:21], v[18:19], off offset:2560
.LBB0_923:
	v_mov_b64_e32 v[18:19], v[222:223]
	v_mov_b64_e32 v[20:21], v[224:225]
	s_nop 0
	v_mov_b64_e32 v[26:27], v[226:227]
	v_mov_b64_e32 v[28:29], v[228:229]
	v_mov_b64_e32 v[30:31], v[230:231]
	v_mov_b64_e32 v[32:33], v[232:233]
	v_pk_mul_f32 v[8:9], v[114:115], v[8:9]
	v_pk_mul_f32 v[14:15], v[16:17], v[14:15]
	v_pk_mul_f32 v[10:11], v[24:25], v[10:11]
	v_pk_mul_f32 v[12:13], v[112:113], v[12:13]
	s_and_b64 vcc, exec, s[6:7]
	v_pk_add_f32 v[18:19], v[18:19], 1.0 op_sel_hi:[1,0]
	v_pk_add_f32 v[16:17], v[20:21], 1.0 op_sel_hi:[1,0]
	s_waitcnt lgkmcnt(0)
	v_pk_mul_f32 v[18:19], v[26:27], v[18:19]
	v_pk_mul_f32 v[16:17], v[28:29], v[16:17]
	v_pk_fma_f32 v[8:9], v[18:19], v[8:9], v[30:31]
	v_pk_fma_f32 v[10:11], v[16:17], v[10:11], v[32:33]
	v_pk_fma_f32 v[14:15], v[16:17], v[14:15], v[32:33]
	v_pk_fma_f32 v[12:13], v[18:19], v[12:13], v[30:31]
	s_nop 1
	v_cvt_pk_bf16_f32 v16, v8, v9
	s_nop 1
	v_cvt_pk_bf16_f32 v17, v10, v11
	s_nop 0
	s_nop 1
	v_cvt_pk_bf16_f32 v8, v12, v13
	s_nop 1
	v_cvt_pk_bf16_f32 v9, v14, v15
	global_store_dwordx2 v[58:59], v[16:17], off offset:1024
	s_cbranch_vccnz .LBB0_925
	v_add_co_u32_e32 v10, vcc, 0x7200000, v56
	s_nop 1
	v_addc_co_u32_e32 v11, vcc, 0, v57, vcc
	global_store_dwordx2 v[10:11], v[8:9], off offset:3072
.LBB0_925:
	v_mov_b64_e32 v[8:9], v[234:235]
	v_mov_b64_e32 v[10:11], v[236:237]
	s_nop 0
	v_mov_b64_e32 v[12:13], v[238:239]
	v_mov_b64_e32 v[14:15], v[240:241]
	v_mov_b64_e32 v[16:17], v[242:243]
	v_mov_b64_e32 v[18:19], v[244:245]
	v_mov_b32_e32 v20, v114
	v_mov_b32_e32 v21, v114
	v_pk_mul_f32 v[0:1], v[114:115], v[0:1]
	v_mov_b32_e32 v22, v112
	v_mov_b32_e32 v23, v112
	v_pk_mul_f32 v[4:5], v[112:113], v[4:5]
	v_pk_mul_f32 v[2:3], v[20:21], v[2:3]
	v_pk_mul_f32 v[6:7], v[22:23], v[6:7]
	s_and_b64 vcc, exec, s[6:7]
	v_pk_add_f32 v[8:9], v[8:9], 1.0 op_sel_hi:[1,0]
	v_pk_add_f32 v[10:11], v[10:11], 1.0 op_sel_hi:[1,0]
	s_waitcnt lgkmcnt(0)
	v_pk_mul_f32 v[8:9], v[12:13], v[8:9]
	v_pk_mul_f32 v[10:11], v[14:15], v[10:11]
	v_pk_fma_f32 v[0:1], v[8:9], v[0:1], v[16:17]
	v_pk_fma_f32 v[2:3], v[10:11], v[2:3], v[18:19]
	v_pk_fma_f32 v[6:7], v[10:11], v[6:7], v[18:19]
	v_pk_fma_f32 v[4:5], v[8:9], v[4:5], v[16:17]
	s_nop 1
	v_cvt_pk_bf16_f32 v8, v0, v1
	s_nop 1
	v_cvt_pk_bf16_f32 v9, v2, v3
	s_nop 0
	s_nop 1
	v_cvt_pk_bf16_f32 v0, v4, v5
	s_nop 1
	v_cvt_pk_bf16_f32 v1, v6, v7
	global_store_dwordx2 v[58:59], v[8:9], off offset:1536
	s_cbranch_vccnz .LBB0_910
	v_add_co_u32_e32 v2, vcc, 0x7200000, v56
	s_nop 1
	v_addc_co_u32_e32 v3, vcc, 0, v57, vcc
	global_store_dwordx2 v[2:3], v[0:1], off offset:3584
	s_branch .LBB0_910

.LBB0_1156:
	s_or_b64 exec, exec, s[6:7]
	s_waitcnt lgkmcnt(0)
	v_mov_b32_e32 v0, v254
	v_mov_b64_e32 v[2:3], s[40:41]
	s_barrier
	flat_load_dwordx2 v[2:3], v[2:3] offset:48 sc0 sc1
	s_waitcnt vmcnt(0)
	v_readfirstlane_b32 s0, v0
	s_ashr_i32 s6, s0, 6
	v_readlane_b32 s0, v255, 6
	s_add_i32 s0, s6, s0
	s_cmpk_lt_i32 s0, 0x2000
	s_waitcnt lgkmcnt(0)
	v_readfirstlane_b32 s1, v3
	v_readfirstlane_b32 s7, v2
	s_cbranch_scc0 .LBB0_1175
	v_lshlrev_b32_e32 v1, 4, v0
	v_and_b32_e32 v64, 0x3f0, v1
	v_mbcnt_lo_u32_b32 v1, -1, 0
	v_mbcnt_hi_u32_b32 v1, -1, v1
	v_and_b32_e32 v2, 64, v1
	v_add_u32_e32 v2, 64, v2
	v_xor_b32_e32 v3, 1, v1
	v_cmp_lt_i32_e32 vcc, v3, v2
	s_add_u32 s8, s7, 0x2000
	s_addc_u32 s9, s1, 0
	v_cndmask_b32_e32 v3, v1, v3, vcc
	v_lshlrev_b32_e32 v122, 2, v3
	v_xor_b32_e32 v3, 2, v1
	v_cmp_lt_i32_e32 vcc, v3, v2
	s_add_u32 s10, s26, 0x1a000
	s_addc_u32 s11, s27, 0
	v_cndmask_b32_e32 v3, v1, v3, vcc
	v_lshlrev_b32_e32 v123, 2, v3
	v_xor_b32_e32 v3, 4, v1
	v_cmp_lt_i32_e32 vcc, v3, v2
	s_add_u32 s12, s26, 0x18000
	v_mov_b32_e32 v65, 0
	v_cndmask_b32_e32 v3, v1, v3, vcc
	v_lshlrev_b32_e32 v124, 2, v3
	v_xor_b32_e32 v3, 8, v1
	v_cmp_lt_i32_e32 vcc, v3, v2
	s_load_dwordx2 s[4:5], s[88:89], 0x168
	s_addc_u32 s13, s27, 0
	v_cndmask_b32_e32 v3, v1, v3, vcc
	v_lshlrev_b32_e32 v125, 2, v3
	v_xor_b32_e32 v3, 16, v1
	v_cmp_lt_i32_e32 vcc, v3, v2
	s_waitcnt lgkmcnt(0)
	v_lshl_add_u64 v[66:67], s[4:5], 0, v[64:65]
	v_lshl_add_u64 v[68:69], s[8:9], 0, v[64:65]
	v_cndmask_b32_e32 v3, v1, v3, vcc
	v_lshlrev_b32_e32 v126, 2, v3
	v_xor_b32_e32 v3, 32, v1
	v_cmp_lt_i32_e32 vcc, v3, v2
	v_or_b32_e32 v2, 0x400, v64
	v_lshl_add_u64 v[70:71], s[10:11], 0, v[64:65]
	v_cndmask_b32_e32 v1, v1, v3, vcc
	v_mov_b32_e32 v3, v65
	v_lshl_add_u64 v[74:75], s[8:9], 0, v[2:3]
	v_lshl_add_u64 v[76:77], s[10:11], 0, v[2:3]
	v_lshl_add_u64 v[78:79], s[12:13], 0, v[2:3]
	v_or_b32_e32 v2, 0x800, v64
	v_lshl_add_u64 v[80:81], s[8:9], 0, v[2:3]
	v_lshl_add_u64 v[82:83], s[10:11], 0, v[2:3]
	v_lshl_add_u64 v[84:85], s[12:13], 0, v[2:3]
	v_or_b32_e32 v2, 0xc00, v64
	v_lshl_add_u64 v[86:87], s[8:9], 0, v[2:3]
	v_lshl_add_u64 v[88:89], s[10:11], 0, v[2:3]
	v_lshl_add_u64 v[90:91], s[12:13], 0, v[2:3]
	v_or_b32_e32 v2, 0x1000, v64
	v_lshl_add_u64 v[92:93], s[8:9], 0, v[2:3]
	v_lshl_add_u64 v[94:95], s[10:11], 0, v[2:3]
	v_lshl_add_u64 v[96:97], s[12:13], 0, v[2:3]
	v_or_b32_e32 v2, 0x1400, v64
	v_lshl_add_u64 v[72:73], s[12:13], 0, v[64:65]
	v_lshl_add_u64 v[98:99], s[8:9], 0, v[2:3]
	v_lshl_add_u64 v[100:101], s[10:11], 0, v[2:3]
	v_lshl_add_u64 v[102:103], s[12:13], 0, v[2:3]
	v_or_b32_e32 v2, 0x1800, v64
	v_or_b32_e32 v64, 0x1c00, v64
	v_lshl_add_u64 v[104:105], s[8:9], 0, v[2:3]
	v_lshl_add_u64 v[110:111], s[8:9], 0, v[64:65]
	s_add_i32 s8, s0, s22
	s_ashr_i32 s9, s8, 31
	s_lshl_b64 s[8:9], s[8:9], 12
	v_lshl_add_u64 v[106:107], s[10:11], 0, v[2:3]
	v_lshl_add_u64 v[112:113], s[10:11], 0, v[64:65]
	s_add_u32 s10, s26, s8
	s_addc_u32 s11, s27, s9
	s_ashr_i32 s53, s52, 31
	v_readlane_b32 s9, v255, 6
	v_lshl_add_u64 v[108:109], s[12:13], 0, v[2:3]
	v_lshl_add_u64 v[114:115], s[12:13], 0, v[64:65]
	s_lshl_b64 s[12:13], s[52:53], 12
	s_ashr_i32 s7, s6, 31
	s_ashr_i32 s8, s9, 31
	s_add_u32 s6, s6, s9
	s_addc_u32 s7, s7, s8
	s_lshl_b64 s[8:9], s[6:7], 12
	s_add_u32 s8, s26, s8
	s_addc_u32 s9, s27, s9
	s_add_u32 s14, s8, 0x7200800
	s_addc_u32 s15, s9, 0
	s_lshl_b64 s[6:7], s[6:7], 13
	v_and_b32_e32 v0, 63, v0
	s_add_u32 s4, s4, s6
	v_lshlrev_b32_e32 v127, 2, v1
	v_lshlrev_b32_e32 v64, 3, v0
	v_lshlrev_b32_e32 v0, 4, v0
	v_mov_b32_e32 v1, v65
	s_addc_u32 s5, s5, s7
	v_lshl_add_u64 v[0:1], s[4:5], 0, v[0:1]
	s_mov_b64 s[4:5], 0x1c00
	s_movk_i32 s1, 0x1000
	v_lshl_add_u64 v[116:117], v[0:1], 0, s[4:5]
	s_lshl_b64 s[16:17], s[52:53], 13
	v_mov_b32_e32 v128, 0x358637bd
	s_mov_b32 s4, 0xf800000
	v_mov_b32_e32 v129, 0x260
	flat_load_dwordx4 v[150:153], v[68:69]
	global_load_dwordx4 v[154:157], v[70:71], off
	global_load_dwordx4 v[158:161], v[72:73], off
	global_load_dwordx4 v[162:165], v[76:77], off
	flat_load_dwordx4 v[166:169], v[74:75]
	global_load_dwordx4 v[170:173], v[78:79], off
	global_load_dwordx4 v[174:177], v[82:83], off
	flat_load_dwordx4 v[178:181], v[80:81]
	global_load_dwordx4 v[182:185], v[84:85], off
	global_load_dwordx4 v[186:189], v[88:89], off
	flat_load_dwordx4 v[190:193], v[86:87]
	global_load_dwordx4 v[194:197], v[90:91], off
	global_load_dwordx4 v[198:201], v[94:95], off
	flat_load_dwordx4 v[202:205], v[92:93]
	global_load_dwordx4 v[206:209], v[96:97], off
	global_load_dwordx4 v[210:213], v[100:101], off
	flat_load_dwordx4 v[214:217], v[98:99]
	global_load_dwordx4 v[218:221], v[102:103], off
	global_load_dwordx4 v[222:225], v[106:107], off
	flat_load_dwordx4 v[226:229], v[104:105]
	global_load_dwordx4 v[230:233], v[108:109], off
	global_load_dwordx4 v[234:237], v[112:113], off
	flat_load_dwordx4 v[238:241], v[110:111]
	global_load_dwordx4 v[242:245], v[114:115], off
	s_waitcnt vmcnt(0) lgkmcnt(0)
	s_branch .LBB0_1159

.LBB0_1159:
	v_add_co_u32_e32 v4, vcc, 0xfffff000, v116
	s_add_i32 s5, s22, s0
	s_nop 0
	v_addc_co_u32_e32 v5, vcc, -1, v117, vcc
	s_cmpk_lt_i32 s5, 0x2000
	global_load_dwordx4 v[32:35], v[116:117], off offset:-4096
	global_load_dwordx4 v[24:27], v[116:117], off offset:-3072
	global_load_dwordx4 v[16:19], v[116:117], off offset:-2048
	global_load_dwordx4 v[8:11], v[116:117], off offset:-1024
	global_load_dwordx4 v[0:3], v[116:117], off
	global_load_dwordx4 v[56:59], v[4:5], off offset:-3072
	global_load_dwordx4 v[48:51], v[4:5], off offset:-2048
	global_load_dwordx4 v[40:43], v[4:5], off offset:-1024
	s_cselect_b64 s[18:19], -1, 0
	s_and_b64 s[6:7], s[18:19], exec
	s_cselect_b32 s6, s5, s0
	s_ashr_i32 s7, s6, 31
	s_lshl_b64 s[6:7], s[6:7], 13
	v_lshl_add_u64 v[4:5], v[66:67], 0, s[6:7]
	global_load_dwordx4 v[60:63], v[4:5], off
	global_load_dwordx4 v[52:55], v[4:5], off offset:1024
	global_load_dwordx4 v[44:47], v[4:5], off offset:2048
	global_load_dwordx4 v[36:39], v[4:5], off offset:3072
	v_add_co_u32_e32 v4, vcc, s1, v4
	s_cmpk_gt_i32 s5, 0x1fff
	s_nop 0
	v_addc_co_u32_e32 v5, vcc, 0, v5, vcc
	global_load_dwordx4 v[28:31], v[4:5], off
	global_load_dwordx4 v[20:23], v[4:5], off offset:1024
	global_load_dwordx4 v[12:15], v[4:5], off offset:2048
	s_nop 0
	global_load_dwordx4 v[4:7], v[4:5], off offset:3072
	s_waitcnt vmcnt(15)
	v_mul_f32_e32 v130, v33, v33
	s_waitcnt vmcnt(14)
	v_mul_f32_e32 v131, v25, v25
	v_fmac_f32_e32 v130, v32, v32
	s_waitcnt vmcnt(10)
	v_mul_f32_e32 v133, v57, v57
	s_waitcnt vmcnt(9)
	v_mul_f32_e32 v134, v49, v49
	s_waitcnt vmcnt(8)
	v_mul_f32_e32 v135, v41, v41
	v_fmac_f32_e32 v133, v56, v56
	v_fmac_f32_e32 v134, v48, v48
	v_fmac_f32_e32 v135, v40, v40
	v_fmac_f32_e32 v133, v58, v58
	v_fmac_f32_e32 v134, v50, v50
	v_fmac_f32_e32 v135, v42, v42
	v_fmac_f32_e32 v133, v59, v59
	v_fmac_f32_e32 v134, v51, v51
	v_fmac_f32_e32 v135, v43, v43
	v_add_f32_e32 v133, v133, v134
	v_mul_f32_e32 v132, v17, v17
	v_fmac_f32_e32 v131, v24, v24
	v_fmac_f32_e32 v130, v34, v34
	v_add_f32_e32 v133, v133, v135
	s_waitcnt vmcnt(7)
	v_mul_f32_e32 v134, v61, v61
	s_waitcnt vmcnt(6)
	v_mul_f32_e32 v135, v53, v53
	v_mov_b32_e32 v120, v9
	v_mov_b32_e32 v121, v1
	v_fmac_f32_e32 v132, v16, v16
	v_fmac_f32_e32 v131, v26, v26
	v_fmac_f32_e32 v130, v35, v35
	s_waitcnt vmcnt(5)
	v_mul_f32_e32 v136, v45, v45
	v_fmac_f32_e32 v134, v60, v60
	v_fmac_f32_e32 v135, v52, v52
	v_mov_b32_e32 v118, v8
	v_mov_b32_e32 v119, v0
	v_pk_mul_f32 v[120:121], v[120:121], v[120:121]
	v_fmac_f32_e32 v132, v18, v18
	v_fmac_f32_e32 v131, v27, v27
	v_add_f32_e32 v130, v133, v130
	s_waitcnt vmcnt(4)
	v_mul_f32_e32 v133, v37, v37
	v_fmac_f32_e32 v136, v44, v44
	v_fmac_f32_e32 v134, v62, v62
	v_fmac_f32_e32 v135, v54, v54
	v_fmac_f32_e32 v132, v19, v19
	v_fmac_f32_e32 v133, v36, v36
	v_add_f32_e32 v130, v130, v131
	v_fmac_f32_e32 v136, v46, v46
	s_waitcnt vmcnt(3)
	v_mul_f32_e32 v131, v29, v29
	v_fmac_f32_e32 v134, v63, v63
	v_fmac_f32_e32 v135, v55, v55
	v_pk_fma_f32 v[118:119], v[118:119], v[118:119], v[120:121]
	v_mov_b32_e32 v120, v10
	v_mov_b32_e32 v121, v2
	v_fmac_f32_e32 v133, v38, v38
	v_add_f32_e32 v130, v130, v132
	s_waitcnt vmcnt(2)
	v_mul_f32_e32 v132, v21, v21
	v_fmac_f32_e32 v136, v47, v47
	v_fmac_f32_e32 v131, v28, v28
	v_add_f32_e32 v134, v134, v135
	v_pk_fma_f32 v[118:119], v[120:121], v[120:121], v[118:119]
	v_mov_b32_e32 v120, v11
	v_mov_b32_e32 v121, v3
	v_fmac_f32_e32 v133, v39, v39
	v_fmac_f32_e32 v132, v20, v20
	v_fmac_f32_e32 v131, v30, v30
	v_add_f32_e32 v134, v134, v136
	v_pk_fma_f32 v[118:119], v[120:121], v[120:121], v[118:119]
	v_fmac_f32_e32 v132, v22, v22
	v_fmac_f32_e32 v131, v31, v31
	v_add_f32_e32 v133, v134, v133
	v_add_f32_e32 v118, v130, v118
	v_fmac_f32_e32 v132, v23, v23
	v_add_f32_e32 v131, v133, v131
	v_add_f32_e32 v130, v118, v119
	v_add_f32_e32 v131, v131, v132
	ds_bpermute_b32 v132, v122, v130
	s_waitcnt vmcnt(1)
	v_mov_b32_e32 v120, v13
	s_waitcnt vmcnt(0)
	v_mov_b32_e32 v121, v5
	v_mov_b32_e32 v118, v12
	v_mov_b32_e32 v119, v4
	s_waitcnt lgkmcnt(0)
	v_add_f32_e32 v130, v130, v132
	ds_bpermute_b32 v132, v123, v130
	v_pk_mul_f32 v[120:121], v[120:121], v[120:121]
	v_mov_b64_e32 v[134:135], v[150:151]
	v_mov_b64_e32 v[136:137], v[152:153]
	v_pk_fma_f32 v[118:119], v[118:119], v[118:119], v[120:121]
	v_mov_b32_e32 v120, v14
	v_mov_b32_e32 v121, v6
	v_pk_fma_f32 v[118:119], v[120:121], v[120:121], v[118:119]
	v_mov_b32_e32 v120, v15
	v_mov_b32_e32 v121, v7
	v_pk_fma_f32 v[118:119], v[120:121], v[120:121], v[118:119]
	s_waitcnt lgkmcnt(0)
	v_add_f32_e32 v120, v130, v132
	v_add_f32_e32 v118, v131, v118
	v_mov_b64_e32 v[130:131], v[154:155]
	v_mov_b64_e32 v[132:133], v[156:157]
	v_mov_b64_e32 v[138:139], v[158:159]
	v_mov_b64_e32 v[140:141], v[160:161]
	ds_bpermute_b32 v121, v124, v120
	v_add_f32_e32 v118, v118, v119
	ds_bpermute_b32 v119, v122, v118
	s_waitcnt lgkmcnt(0)
	v_add_f32_e32 v120, v120, v121
	ds_bpermute_b32 v121, v125, v120
	v_add_f32_e32 v118, v118, v119
	ds_bpermute_b32 v119, v123, v118
	s_waitcnt lgkmcnt(0)
	v_add_f32_e32 v120, v120, v121
	ds_bpermute_b32 v121, v126, v120
	v_add_f32_e32 v118, v118, v119
	ds_bpermute_b32 v119, v124, v118
	s_waitcnt lgkmcnt(0)
	v_add_f32_e32 v120, v120, v121
	ds_bpermute_b32 v121, v127, v120
	v_add_f32_e32 v118, v118, v119
	ds_bpermute_b32 v119, v125, v118
	s_waitcnt lgkmcnt(0)
	v_add_f32_e32 v120, v120, v121
	v_fmamk_f32 v120, v120, 0x3a000000, v128
	v_mul_f32_e32 v121, 0x4f800000, v120
	v_cmp_gt_f32_e32 vcc, s4, v120
	v_add_f32_e32 v118, v118, v119
	ds_bpermute_b32 v119, v126, v118
	v_cndmask_b32_e32 v120, v120, v121, vcc
	v_sqrt_f32_e32 v121, v120
	s_waitcnt lgkmcnt(0)
	v_add_f32_e32 v118, v118, v119
	v_add_u32_e32 v142, -1, v121
	v_fma_f32 v143, -v142, v121, v120
	v_cmp_ge_f32_e64 s[6:7], 0, v143
	v_add_u32_e32 v143, 1, v121
	ds_bpermute_b32 v119, v127, v118
	v_cndmask_b32_e64 v142, v121, v142, s[6:7]
	v_fma_f32 v121, -v143, v121, v120
	v_cmp_lt_f32_e64 s[6:7], 0, v121
	s_waitcnt lgkmcnt(0)
	v_add_f32_e32 v118, v118, v119
	v_cndmask_b32_e64 v121, v142, v143, s[6:7]
	v_mul_f32_e32 v142, 0x37800000, v121
	v_cndmask_b32_e32 v121, v121, v142, vcc
	v_cmp_class_f32_e32 vcc, v120, v129
	v_fmamk_f32 v118, v118, 0x3a000000, v128
	v_mul_f32_e32 v144, 0x4f800000, v118
	v_cndmask_b32_e32 v120, v121, v120, vcc
	v_div_scale_f32 v121, s[6:7], v120, v120, 1.0
	v_rcp_f32_e32 v142, v121
	v_cmp_gt_f32_e64 s[6:7], s4, v118
	v_fma_f32 v119, -v121, v142, 1.0
	s_nop 0
	v_cndmask_b32_e64 v118, v118, v144, s[6:7]
	v_fmac_f32_e32 v142, v119, v142
	v_div_scale_f32 v119, vcc, 1.0, v120, 1.0
	v_sqrt_f32_e32 v144, v118
	v_mul_f32_e32 v143, v119, v142
	v_fma_f32 v145, -v121, v143, v119
	v_fmac_f32_e32 v143, v145, v142
	v_fma_f32 v119, -v121, v143, v119
	v_add_u32_e32 v121, -1, v144
	v_fma_f32 v145, -v121, v144, v118
	v_cmp_ge_f32_e64 s[8:9], 0, v145
	v_add_u32_e32 v145, 1, v144
	v_div_fmas_f32 v119, v119, v142, v143
	v_cndmask_b32_e64 v121, v144, v121, s[8:9]
	v_fma_f32 v144, -v145, v144, v118
	v_cmp_lt_f32_e64 s[8:9], 0, v144
	v_div_fixup_f32 v120, v119, v120, 1.0
	v_pk_add_f32 v[132:133], v[132:133], 1.0 op_sel_hi:[1,0]
	v_cndmask_b32_e64 v121, v121, v145, s[8:9]
	v_mul_f32_e32 v144, 0x37800000, v121
	v_cndmask_b32_e64 v121, v121, v144, s[6:7]
	v_cmp_class_f32_e64 s[6:7], v118, v129
	v_pk_add_f32 v[130:131], v[130:131], 1.0 op_sel_hi:[1,0]
	v_pk_mul_f32 v[132:133], v[136:137], v[132:133]
	v_cndmask_b32_e64 v118, v121, v118, s[6:7]
	v_div_scale_f32 v121, s[6:7], v118, v118, 1.0
	v_rcp_f32_e32 v144, v121
	v_pk_mul_f32 v[130:131], v[134:135], v[130:131]
	v_pk_mul_f32 v[56:57], v[120:121], v[56:57] op_sel_hi:[0,1]
	v_pk_mul_f32 v[58:59], v[120:121], v[58:59] op_sel_hi:[0,1]
	v_fma_f32 v119, -v121, v144, 1.0
	v_fmac_f32_e32 v144, v119, v144
	v_div_scale_f32 v119, vcc, 1.0, v118, 1.0
	v_mul_f32_e32 v142, v119, v144
	v_fma_f32 v143, -v121, v142, v119
	v_fmac_f32_e32 v142, v143, v144
	v_fma_f32 v119, -v121, v142, v119
	v_div_fmas_f32 v119, v119, v144, v142
	v_div_fixup_f32 v118, v119, v118, 1.0
	v_pk_fma_f32 v[58:59], v[132:133], v[58:59], v[140:141]
	v_pk_fma_f32 v[56:57], v[130:131], v[56:57], v[138:139]
	v_pk_mul_f32 v[60:61], v[118:119], v[60:61] op_sel_hi:[0,1]
	v_pk_mul_f32 v[62:63], v[118:119], v[62:63] op_sel_hi:[0,1]
	v_pk_fma_f32 v[60:61], v[130:131], v[60:61], v[138:139]
	s_nop 1
	v_cvt_pk_bf16_f32 v56, v56, v57
	s_nop 1
	v_cvt_pk_bf16_f32 v57, v58, v59
	v_lshl_add_u64 v[58:59], s[14:15], 0, v[64:65]
	v_pk_fma_f32 v[62:63], v[132:133], v[62:63], v[140:141]
	s_nop 1
	v_cvt_pk_bf16_f32 v60, v60, v61
	s_nop 0
	s_nop 1
	v_cvt_pk_bf16_f32 v61, v62, v63
	global_store_dwordx2 v[58:59], v[56:57], off offset:-2048
	v_lshl_add_u64 v[56:57], s[10:11], 0, v[64:65]
	s_cbranch_scc1 .LBB0_1161
	v_add_co_u32_e32 v62, vcc, 0x7200000, v56
	s_nop 1
	v_addc_co_u32_e32 v63, vcc, 0, v57, vcc
	global_store_dwordx2 v[62:63], v[60:61], off
.LBB0_1161:
	v_mov_b64_e32 v[130:131], v[162:163]
	v_mov_b64_e32 v[132:133], v[164:165]
	v_mov_b64_e32 v[134:135], v[166:167]
	v_mov_b64_e32 v[136:137], v[168:169]
	v_mov_b64_e32 v[138:139], v[170:171]
	v_mov_b64_e32 v[140:141], v[172:173]
	v_mov_b32_e32 v121, v120
	v_mov_b32_e32 v119, v118
	v_mov_b32_e32 v60, v120
	v_mov_b32_e32 v61, v120
	v_mov_b32_e32 v62, v118
	v_mov_b32_e32 v63, v118
	v_cndmask_b32_e64 v142, 0, 1, s[18:19]
	v_pk_mul_f32 v[48:49], v[120:121], v[48:49]
	v_pk_mul_f32 v[50:51], v[60:61], v[50:51]
	v_pk_mul_f32 v[54:55], v[62:63], v[54:55]
	v_pk_mul_f32 v[52:53], v[118:119], v[52:53]
	v_cmp_ne_u32_e64 s[6:7], 1, v142
	s_andn2_b64 vcc, exec, s[18:19]
	v_pk_add_f32 v[130:131], v[130:131], 1.0 op_sel_hi:[1,0]
	v_pk_add_f32 v[132:133], v[132:133], 1.0 op_sel_hi:[1,0]
	s_waitcnt lgkmcnt(0)
	v_pk_mul_f32 v[130:131], v[134:135], v[130:131]
	v_pk_mul_f32 v[132:133], v[136:137], v[132:133]
	v_pk_fma_f32 v[48:49], v[130:131], v[48:49], v[138:139]
	v_pk_fma_f32 v[50:51], v[132:133], v[50:51], v[140:141]
	v_pk_fma_f32 v[54:55], v[132:133], v[54:55], v[140:141]
	v_pk_fma_f32 v[52:53], v[130:131], v[52:53], v[138:139]
	s_nop 1
	v_cvt_pk_bf16_f32 v130, v48, v49
	s_nop 1
	v_cvt_pk_bf16_f32 v131, v50, v51
	s_nop 0
	s_nop 1
	v_cvt_pk_bf16_f32 v48, v52, v53
	s_nop 1
	v_cvt_pk_bf16_f32 v49, v54, v55
	global_store_dwordx2 v[58:59], v[130:131], off offset:-1536
	s_cbranch_vccnz .LBB0_1163
	v_add_co_u32_e32 v50, vcc, 0x7200000, v56
	s_nop 1
	v_addc_co_u32_e32 v51, vcc, 0, v57, vcc
	global_store_dwordx2 v[50:51], v[48:49], off offset:512
.LBB0_1163:
	v_mov_b64_e32 v[48:49], v[174:175]
	v_mov_b64_e32 v[50:51], v[176:177]
	s_nop 0
	v_mov_b64_e32 v[52:53], v[178:179]
	v_mov_b64_e32 v[54:55], v[180:181]
	v_mov_b64_e32 v[130:131], v[182:183]
	v_mov_b64_e32 v[132:133], v[184:185]
	v_pk_mul_f32 v[40:41], v[120:121], v[40:41]
	v_pk_mul_f32 v[42:43], v[60:61], v[42:43]
	v_pk_mul_f32 v[46:47], v[62:63], v[46:47]
	v_pk_mul_f32 v[44:45], v[118:119], v[44:45]
	s_and_b64 vcc, exec, s[6:7]
	v_pk_add_f32 v[48:49], v[48:49], 1.0 op_sel_hi:[1,0]
	v_pk_add_f32 v[50:51], v[50:51], 1.0 op_sel_hi:[1,0]
	s_waitcnt lgkmcnt(0)
	v_pk_mul_f32 v[48:49], v[52:53], v[48:49]
	v_pk_mul_f32 v[50:51], v[54:55], v[50:51]
	v_pk_fma_f32 v[40:41], v[48:49], v[40:41], v[130:131]
	v_pk_fma_f32 v[42:43], v[50:51], v[42:43], v[132:133]
	v_pk_fma_f32 v[46:47], v[50:51], v[46:47], v[132:133]
	v_pk_fma_f32 v[44:45], v[48:49], v[44:45], v[130:131]
	s_nop 1
	v_cvt_pk_bf16_f32 v48, v40, v41
	s_nop 1
	v_cvt_pk_bf16_f32 v49, v42, v43
	s_nop 0
	s_nop 1
	v_cvt_pk_bf16_f32 v40, v44, v45
	s_nop 1
	v_cvt_pk_bf16_f32 v41, v46, v47
	global_store_dwordx2 v[58:59], v[48:49], off offset:-1024
	s_cbranch_vccnz .LBB0_1165
	v_add_co_u32_e32 v42, vcc, 0x7200000, v56
	s_nop 1
	v_addc_co_u32_e32 v43, vcc, 0, v57, vcc
	global_store_dwordx2 v[42:43], v[40:41], off offset:1024
.LBB0_1165:
	v_mov_b64_e32 v[42:43], v[186:187]
	v_mov_b64_e32 v[44:45], v[188:189]
	s_nop 0
	v_mov_b64_e32 v[46:47], v[190:191]
	v_mov_b64_e32 v[48:49], v[192:193]
	v_mov_b64_e32 v[50:51], v[194:195]
	v_mov_b64_e32 v[52:53], v[196:197]
	v_mov_b32_e32 v40, v120
	v_mov_b32_e32 v41, v120
	v_pk_mul_f32 v[54:55], v[120:121], v[32:33]
	v_mov_b32_e32 v32, v118
	v_mov_b32_e32 v33, v118
	v_pk_mul_f32 v[34:35], v[40:41], v[34:35]
	v_pk_mul_f32 v[36:37], v[118:119], v[36:37]
	v_pk_mul_f32 v[38:39], v[32:33], v[38:39]
	s_and_b64 vcc, exec, s[6:7]
	v_pk_add_f32 v[44:45], v[44:45], 1.0 op_sel_hi:[1,0]
	v_pk_add_f32 v[42:43], v[42:43], 1.0 op_sel_hi:[1,0]
	s_waitcnt lgkmcnt(0)
	v_pk_mul_f32 v[44:45], v[48:49], v[44:45]
	v_pk_mul_f32 v[42:43], v[46:47], v[42:43]
	v_pk_fma_f32 v[34:35], v[44:45], v[34:35], v[52:53]
	v_pk_fma_f32 v[46:47], v[42:43], v[54:55], v[50:51]
	v_pk_fma_f32 v[38:39], v[44:45], v[38:39], v[52:53]
	v_pk_fma_f32 v[36:37], v[42:43], v[36:37], v[50:51]
	s_nop 1
	v_cvt_pk_bf16_f32 v42, v46, v47
	s_nop 1
	v_cvt_pk_bf16_f32 v43, v34, v35
	s_nop 0
	s_nop 1
	v_cvt_pk_bf16_f32 v34, v36, v37
	s_nop 1
	v_cvt_pk_bf16_f32 v35, v38, v39
	global_store_dwordx2 v[58:59], v[42:43], off offset:-512
	s_cbranch_vccnz .LBB0_1167
	v_add_co_u32_e32 v36, vcc, 0x7200000, v56
	s_nop 1
	v_addc_co_u32_e32 v37, vcc, 0, v57, vcc
	global_store_dwordx2 v[36:37], v[34:35], off offset:1536
.LBB0_1167:
	v_mov_b64_e32 v[34:35], v[198:199]
	v_mov_b64_e32 v[36:37], v[200:201]
	s_nop 0
	v_mov_b64_e32 v[42:43], v[202:203]
	v_mov_b64_e32 v[44:45], v[204:205]
	v_mov_b64_e32 v[46:47], v[206:207]
	v_mov_b64_e32 v[48:49], v[208:209]
	v_pk_mul_f32 v[24:25], v[120:121], v[24:25]
	v_pk_mul_f32 v[30:31], v[32:33], v[30:31]
	v_pk_mul_f32 v[26:27], v[40:41], v[26:27]
	v_pk_mul_f32 v[28:29], v[118:119], v[28:29]
	s_and_b64 vcc, exec, s[6:7]
	v_pk_add_f32 v[34:35], v[34:35], 1.0 op_sel_hi:[1,0]
	v_pk_add_f32 v[32:33], v[36:37], 1.0 op_sel_hi:[1,0]
	s_waitcnt lgkmcnt(0)
	v_pk_mul_f32 v[34:35], v[42:43], v[34:35]
	v_pk_mul_f32 v[32:33], v[44:45], v[32:33]
	v_pk_fma_f32 v[24:25], v[34:35], v[24:25], v[46:47]
	v_pk_fma_f32 v[26:27], v[32:33], v[26:27], v[48:49]
	v_pk_fma_f32 v[30:31], v[32:33], v[30:31], v[48:49]
	v_pk_fma_f32 v[28:29], v[34:35], v[28:29], v[46:47]
	s_nop 1
	v_cvt_pk_bf16_f32 v32, v24, v25
	s_nop 1
	v_cvt_pk_bf16_f32 v33, v26, v27
	s_nop 0
	s_nop 1
	v_cvt_pk_bf16_f32 v24, v28, v29
	s_nop 1
	v_cvt_pk_bf16_f32 v25, v30, v31
	global_store_dwordx2 v[58:59], v[32:33], off
	s_cbranch_vccnz .LBB0_1169
	v_add_co_u32_e32 v26, vcc, 0x7200000, v56
	s_nop 1
	v_addc_co_u32_e32 v27, vcc, 0, v57, vcc
	global_store_dwordx2 v[26:27], v[24:25], off offset:2048
.LBB0_1169:
	v_mov_b64_e32 v[26:27], v[210:211]
	v_mov_b64_e32 v[28:29], v[212:213]
	s_nop 0
	v_mov_b64_e32 v[30:31], v[214:215]
	v_mov_b64_e32 v[32:33], v[216:217]
	v_mov_b64_e32 v[34:35], v[218:219]
	v_mov_b64_e32 v[36:37], v[220:221]
	v_mov_b32_e32 v24, v120
	v_mov_b32_e32 v25, v120
	v_pk_mul_f32 v[38:39], v[120:121], v[16:17]
	v_mov_b32_e32 v16, v118
	v_mov_b32_e32 v17, v118
	v_pk_mul_f32 v[18:19], v[24:25], v[18:19]
	v_pk_mul_f32 v[20:21], v[118:119], v[20:21]
	v_pk_mul_f32 v[22:23], v[16:17], v[22:23]
	s_and_b64 vcc, exec, s[6:7]
	v_pk_add_f32 v[28:29], v[28:29], 1.0 op_sel_hi:[1,0]
	v_pk_add_f32 v[26:27], v[26:27], 1.0 op_sel_hi:[1,0]
	s_waitcnt lgkmcnt(0)
	v_pk_mul_f32 v[28:29], v[32:33], v[28:29]
	v_pk_mul_f32 v[26:27], v[30:31], v[26:27]
	v_pk_fma_f32 v[18:19], v[28:29], v[18:19], v[36:37]
	v_pk_fma_f32 v[30:31], v[26:27], v[38:39], v[34:35]
	v_pk_fma_f32 v[22:23], v[28:29], v[22:23], v[36:37]
	v_pk_fma_f32 v[20:21], v[26:27], v[20:21], v[34:35]
	s_nop 1
	v_cvt_pk_bf16_f32 v26, v30, v31
	s_nop 1
	v_cvt_pk_bf16_f32 v27, v18, v19
	s_nop 0
	s_nop 1
	v_cvt_pk_bf16_f32 v18, v20, v21
	s_nop 1
	v_cvt_pk_bf16_f32 v19, v22, v23
	global_store_dwordx2 v[58:59], v[26:27], off offset:512
	s_cbranch_vccnz .LBB0_1171
	v_add_co_u32_e32 v20, vcc, 0x7200000, v56
	s_nop 1
	v_addc_co_u32_e32 v21, vcc, 0, v57, vcc
	global_store_dwordx2 v[20:21], v[18:19], off offset:2560
.LBB0_1171:
	v_mov_b64_e32 v[18:19], v[222:223]
	v_mov_b64_e32 v[20:21], v[224:225]
	s_nop 0
	v_mov_b64_e32 v[26:27], v[226:227]
	v_mov_b64_e32 v[28:29], v[228:229]
	v_mov_b64_e32 v[30:31], v[230:231]
	v_mov_b64_e32 v[32:33], v[232:233]
	v_pk_mul_f32 v[8:9], v[120:121], v[8:9]
	v_pk_mul_f32 v[14:15], v[16:17], v[14:15]
	v_pk_mul_f32 v[10:11], v[24:25], v[10:11]
	v_pk_mul_f32 v[12:13], v[118:119], v[12:13]
	s_and_b64 vcc, exec, s[6:7]
	v_pk_add_f32 v[18:19], v[18:19], 1.0 op_sel_hi:[1,0]
	v_pk_add_f32 v[16:17], v[20:21], 1.0 op_sel_hi:[1,0]
	s_waitcnt lgkmcnt(0)
	v_pk_mul_f32 v[18:19], v[26:27], v[18:19]
	v_pk_mul_f32 v[16:17], v[28:29], v[16:17]
	v_pk_fma_f32 v[8:9], v[18:19], v[8:9], v[30:31]
	v_pk_fma_f32 v[10:11], v[16:17], v[10:11], v[32:33]
	v_pk_fma_f32 v[14:15], v[16:17], v[14:15], v[32:33]
	v_pk_fma_f32 v[12:13], v[18:19], v[12:13], v[30:31]
	s_nop 1
	v_cvt_pk_bf16_f32 v16, v8, v9
	s_nop 1
	v_cvt_pk_bf16_f32 v17, v10, v11
	s_nop 0
	s_nop 1
	v_cvt_pk_bf16_f32 v8, v12, v13
	s_nop 1
	v_cvt_pk_bf16_f32 v9, v14, v15
	global_store_dwordx2 v[58:59], v[16:17], off offset:1024
	s_cbranch_vccnz .LBB0_1173
	v_add_co_u32_e32 v10, vcc, 0x7200000, v56
	s_nop 1
	v_addc_co_u32_e32 v11, vcc, 0, v57, vcc
	global_store_dwordx2 v[10:11], v[8:9], off offset:3072
.LBB0_1173:
	v_mov_b64_e32 v[8:9], v[234:235]
	v_mov_b64_e32 v[10:11], v[236:237]
	s_nop 0
	v_mov_b64_e32 v[12:13], v[238:239]
	v_mov_b64_e32 v[14:15], v[240:241]
	v_mov_b64_e32 v[16:17], v[242:243]
	v_mov_b64_e32 v[18:19], v[244:245]
	v_mov_b32_e32 v20, v120
	v_mov_b32_e32 v21, v120
	v_pk_mul_f32 v[0:1], v[120:121], v[0:1]
	v_mov_b32_e32 v22, v118
	v_mov_b32_e32 v23, v118
	v_pk_mul_f32 v[4:5], v[118:119], v[4:5]
	v_pk_mul_f32 v[2:3], v[20:21], v[2:3]
	v_pk_mul_f32 v[6:7], v[22:23], v[6:7]
	s_and_b64 vcc, exec, s[6:7]
	v_pk_add_f32 v[8:9], v[8:9], 1.0 op_sel_hi:[1,0]
	v_pk_add_f32 v[10:11], v[10:11], 1.0 op_sel_hi:[1,0]
	s_waitcnt lgkmcnt(0)
	v_pk_mul_f32 v[8:9], v[12:13], v[8:9]
	v_pk_mul_f32 v[10:11], v[14:15], v[10:11]
	v_pk_fma_f32 v[0:1], v[8:9], v[0:1], v[16:17]
	v_pk_fma_f32 v[2:3], v[10:11], v[2:3], v[18:19]
	v_pk_fma_f32 v[6:7], v[10:11], v[6:7], v[18:19]
	v_pk_fma_f32 v[4:5], v[8:9], v[4:5], v[16:17]
	s_nop 1
	v_cvt_pk_bf16_f32 v8, v0, v1
	s_nop 1
	v_cvt_pk_bf16_f32 v9, v2, v3
	s_nop 0
	s_nop 1
	v_cvt_pk_bf16_f32 v0, v4, v5
	s_nop 1
	v_cvt_pk_bf16_f32 v1, v6, v7
	global_store_dwordx2 v[58:59], v[8:9], off offset:1536
	s_cbranch_vccnz .LBB0_1158
	v_add_co_u32_e32 v2, vcc, 0x7200000, v56
	s_nop 1
	v_addc_co_u32_e32 v3, vcc, 0, v57, vcc
	global_store_dwordx2 v[2:3], v[0:1], off offset:3584
	s_branch .LBB0_1158

.LBB0_1598:
	s_or_b64 exec, exec, s[6:7]
	s_waitcnt lgkmcnt(0)
	v_mov_b32_e32 v0, v254
	v_mov_b64_e32 v[2:3], s[58:59]
	s_barrier
	flat_load_dwordx2 v[2:3], v[2:3] offset:56 sc0 sc1
	s_waitcnt vmcnt(0)
	v_readfirstlane_b32 s0, v0
	s_ashr_i32 s6, s0, 6
	v_readlane_b32 s0, v255, 6
	s_add_i32 s0, s6, s0
	s_cmpk_lt_i32 s0, 0x2000
	s_waitcnt lgkmcnt(0)
	v_readfirstlane_b32 s1, v3
	v_readfirstlane_b32 s7, v2
	s_cbranch_scc0 .LBB0_1617
	v_lshlrev_b32_e32 v1, 4, v0
	v_and_b32_e32 v64, 0x3f0, v1
	v_mbcnt_lo_u32_b32 v1, -1, 0
	v_mbcnt_hi_u32_b32 v1, -1, v1
	v_and_b32_e32 v2, 64, v1
	v_add_u32_e32 v2, 64, v2
	v_xor_b32_e32 v3, 1, v1
	v_cmp_lt_i32_e32 vcc, v3, v2
	s_add_u32 s8, s7, 0x2000
	s_addc_u32 s9, s1, 0
	v_cndmask_b32_e32 v3, v1, v3, vcc
	v_lshlrev_b32_e32 v122, 2, v3
	v_xor_b32_e32 v3, 2, v1
	v_cmp_lt_i32_e32 vcc, v3, v2
	s_add_u32 s10, s26, 0x1e000
	s_addc_u32 s11, s27, 0
	v_cndmask_b32_e32 v3, v1, v3, vcc
	v_lshlrev_b32_e32 v123, 2, v3
	v_xor_b32_e32 v3, 4, v1
	v_cmp_lt_i32_e32 vcc, v3, v2
	s_add_u32 s12, s26, 0x20000
	v_mov_b32_e32 v65, 0
	v_cndmask_b32_e32 v3, v1, v3, vcc
	v_lshlrev_b32_e32 v124, 2, v3
	v_xor_b32_e32 v3, 8, v1
	v_cmp_lt_i32_e32 vcc, v3, v2
	s_load_dwordx2 s[4:5], s[88:89], 0x168
	s_addc_u32 s13, s27, 0
	v_cndmask_b32_e32 v3, v1, v3, vcc
	v_lshlrev_b32_e32 v125, 2, v3
	v_xor_b32_e32 v3, 16, v1
	v_cmp_lt_i32_e32 vcc, v3, v2
	s_waitcnt lgkmcnt(0)
	v_lshl_add_u64 v[66:67], s[4:5], 0, v[64:65]
	v_lshl_add_u64 v[68:69], s[8:9], 0, v[64:65]
	v_cndmask_b32_e32 v3, v1, v3, vcc
	v_lshlrev_b32_e32 v126, 2, v3
	v_xor_b32_e32 v3, 32, v1
	v_cmp_lt_i32_e32 vcc, v3, v2
	v_or_b32_e32 v2, 0x400, v64
	v_lshl_add_u64 v[70:71], s[12:13], 0, v[64:65]
	v_cndmask_b32_e32 v1, v1, v3, vcc
	v_mov_b32_e32 v3, v65
	v_lshl_add_u64 v[74:75], s[8:9], 0, v[2:3]
	v_lshl_add_u64 v[76:77], s[12:13], 0, v[2:3]
	v_lshl_add_u64 v[78:79], s[10:11], 0, v[2:3]
	v_or_b32_e32 v2, 0x800, v64
	v_lshl_add_u64 v[80:81], s[8:9], 0, v[2:3]
	v_lshl_add_u64 v[82:83], s[12:13], 0, v[2:3]
	v_lshl_add_u64 v[84:85], s[10:11], 0, v[2:3]
	v_or_b32_e32 v2, 0xc00, v64
	v_lshl_add_u64 v[86:87], s[8:9], 0, v[2:3]
	v_lshl_add_u64 v[88:89], s[12:13], 0, v[2:3]
	v_lshl_add_u64 v[90:91], s[10:11], 0, v[2:3]
	v_or_b32_e32 v2, 0x1000, v64
	v_lshl_add_u64 v[92:93], s[8:9], 0, v[2:3]
	v_lshl_add_u64 v[94:95], s[12:13], 0, v[2:3]
	v_lshl_add_u64 v[96:97], s[10:11], 0, v[2:3]
	v_or_b32_e32 v2, 0x1400, v64
	v_lshl_add_u64 v[72:73], s[10:11], 0, v[64:65]
	v_lshl_add_u64 v[98:99], s[8:9], 0, v[2:3]
	v_lshl_add_u64 v[100:101], s[12:13], 0, v[2:3]
	v_lshl_add_u64 v[102:103], s[10:11], 0, v[2:3]
	v_or_b32_e32 v2, 0x1800, v64
	v_or_b32_e32 v64, 0x1c00, v64
	v_lshl_add_u64 v[104:105], s[8:9], 0, v[2:3]
	v_lshl_add_u64 v[110:111], s[8:9], 0, v[64:65]
	s_add_i32 s8, s0, s22
	s_ashr_i32 s9, s8, 31
	s_lshl_b64 s[8:9], s[8:9], 12
	v_lshl_add_u64 v[108:109], s[10:11], 0, v[2:3]
	v_lshl_add_u64 v[114:115], s[10:11], 0, v[64:65]
	s_add_u32 s10, s26, s8
	s_addc_u32 s11, s27, s9
	s_ashr_i32 s53, s52, 31
	v_readlane_b32 s9, v255, 6
	v_lshl_add_u64 v[106:107], s[12:13], 0, v[2:3]
	v_lshl_add_u64 v[112:113], s[12:13], 0, v[64:65]
	s_lshl_b64 s[12:13], s[52:53], 12
	s_ashr_i32 s7, s6, 31
	s_ashr_i32 s8, s9, 31
	s_add_u32 s6, s6, s9
	s_addc_u32 s7, s7, s8
	s_lshl_b64 s[8:9], s[6:7], 12
	s_add_u32 s8, s26, s8
	s_addc_u32 s9, s27, s9
	s_add_u32 s14, s8, 0x7200800
	s_addc_u32 s15, s9, 0
	s_lshl_b64 s[6:7], s[6:7], 13
	v_and_b32_e32 v0, 63, v0
	s_add_u32 s4, s4, s6
	v_lshlrev_b32_e32 v127, 2, v1
	v_lshlrev_b32_e32 v64, 3, v0
	v_lshlrev_b32_e32 v0, 4, v0
	v_mov_b32_e32 v1, v65
	s_addc_u32 s5, s5, s7
	v_lshl_add_u64 v[0:1], s[4:5], 0, v[0:1]
	s_mov_b64 s[4:5], 0x1c00
	s_movk_i32 s1, 0x1000
	v_lshl_add_u64 v[116:117], v[0:1], 0, s[4:5]
	s_lshl_b64 s[16:17], s[52:53], 13
	v_mov_b32_e32 v128, 0x358637bd
	s_mov_b32 s4, 0xf800000
	v_mov_b32_e32 v129, 0x260
	flat_load_dwordx4 v[150:153], v[68:69]
	global_load_dwordx4 v[154:157], v[70:71], off
	global_load_dwordx4 v[158:161], v[72:73], off
	global_load_dwordx4 v[162:165], v[76:77], off
	flat_load_dwordx4 v[166:169], v[74:75]
	global_load_dwordx4 v[170:173], v[78:79], off
	global_load_dwordx4 v[174:177], v[82:83], off
	flat_load_dwordx4 v[178:181], v[80:81]
	global_load_dwordx4 v[182:185], v[84:85], off
	global_load_dwordx4 v[186:189], v[88:89], off
	flat_load_dwordx4 v[190:193], v[86:87]
	global_load_dwordx4 v[194:197], v[90:91], off
	global_load_dwordx4 v[198:201], v[94:95], off
	flat_load_dwordx4 v[202:205], v[92:93]
	global_load_dwordx4 v[206:209], v[96:97], off
	global_load_dwordx4 v[210:213], v[100:101], off
	flat_load_dwordx4 v[214:217], v[98:99]
	global_load_dwordx4 v[218:221], v[102:103], off
	global_load_dwordx4 v[222:225], v[106:107], off
	flat_load_dwordx4 v[226:229], v[104:105]
	global_load_dwordx4 v[230:233], v[108:109], off
	global_load_dwordx4 v[234:237], v[112:113], off
	flat_load_dwordx4 v[238:241], v[110:111]
	global_load_dwordx4 v[242:245], v[114:115], off
	s_waitcnt vmcnt(0) lgkmcnt(0)
	s_branch .LBB0_1601
